# L row-sum MFMAs moved to the end of each PV block (after the O MFMAs)
# baseline (speedup 1.0000x reference)
; #define LAS __attribute__((address_space(3)))
; #define MFMA32(a, b, c) __builtin_amdgcn_mfma_f32_32x32x16_bf16((a), (b), (c), 0, 0, 0)
; __device__ __forceinline__ void at_pv_half(const LAS unsigned char* vp, const bf16x8 (&pf)[4], f32x16 (&O)[4], f32x16& L) {
;     bf16x8 va[8], vb[8];
; #pragma unroll
;     for (int e = 0; e < 2; ++e)
; #pragma unroll
;         for (int ks = 0; ks < 4; ++ks) va[e * 4 + ks] = *(const LAS bf16x8*)(vp + e * 32 * AT_ROWB + 32 * ks);
; #pragma unroll
;     for (int e = 0; e < 2; ++e)
; #pragma unroll
;         for (int ks = 0; ks < 4; ++ks) vb[e * 4 + ks] = *(const LAS bf16x8*)(vp + (2 + e) * 32 * AT_ROWB + 32 * ks);
;     const short one = (short)0x3F80; const bf16x8 ones = {one, one, one, one, one, one, one, one};
;     __builtin_amdgcn_sched_barrier(0);
;     __builtin_amdgcn_s_setprio(1);
; #pragma unroll
;     for (int ks = 0; ks < 4; ++ks) L = MFMA32(ones, pf[ks], L);
;     __builtin_amdgcn_sched_barrier(0);
; #pragma unroll
;     for (int ks = 0; ks < 4; ++ks) { O[0] = MFMA32(va[ks], pf[ks], O[0]); O[1] = MFMA32(va[4 + ks], pf[ks], O[1]); }
; #pragma unroll
;     for (int ks = 0; ks < 4; ++ks) { O[2] = MFMA32(vb[ks], pf[ks], O[2]); O[3] = MFMA32(vb[4 + ks], pf[ks], O[3]); }
;     __builtin_amdgcn_s_setprio(0);
; }
.LBB0_295:
	s_add_i32 s44, s45, 1
	s_bitcmp1_b32 s44, 0
	s_cselect_b32 s53, 0x4800, 0
	s_min_i32 s58, s44, s41
	s_lshl_b64 s[54:55], s[58:59], 14
	v_lshl_add_u64 v[96:97], v[208:209], 0, s[54:55]
	v_lshl_add_u64 v[98:99], v[210:211], 0, s[54:55]
	global_load_dwordx4 v[146:149], v[96:97], off
	global_load_dwordx4 v[150:153], v[98:99], off
	s_add_i32 s56, s53, 0
	s_cmp_eq_u32 s45, 0
	s_cselect_b64 s[54:55], -1, 0
	s_add_i32 s53, s1, 0xffffff81
	s_cmp_gt_i32 s53, s40
	s_cselect_b64 s[60:61], -1, 0
	s_or_b64 s[54:55], s[54:55], s[60:61]
	s_and_b64 vcc, exec, s[54:55]
	s_cbranch_vccnz .LBB0_297
	v_add_u32_e32 v184, s56, v228
	ds_read_b128 v[96:99], v184 offset:36864
	ds_read_b128 v[100:103], v184 offset:36896
	ds_read_b128 v[104:107], v184 offset:36928
	ds_read_b128 v[108:111], v184 offset:36960
	ds_read_b128 v[154:157], v184 offset:41472
	ds_read_b128 v[158:161], v184 offset:41504
	ds_read_b128 v[162:165], v184 offset:41536
	ds_read_b128 v[166:169], v184 offset:41568
	ds_read_b128 v[170:173], v184 offset:46080
	ds_read_b128 v[174:177], v184 offset:46112
	ds_read_b128 v[178:181], v184 offset:46144
	ds_read_b128 v[232:235], v184 offset:46176
	ds_read_b128 v[236:239], v184 offset:50688
	ds_read_b128 v[240:243], v184 offset:50720
	ds_read_b128 v[244:247], v184 offset:50752
	ds_read_b128 v[248:251], v184 offset:50784
	s_setprio 1
	s_waitcnt lgkmcnt(14)
	v_mfma_f32_32x32x16_bf16 v[48:63], v[96:99], v[80:83], v[48:63]
	s_waitcnt lgkmcnt(11)
	v_mfma_f32_32x32x16_bf16 v[32:47], v[154:157], v[80:83], v[32:47]
	s_waitcnt lgkmcnt(7)
	v_mfma_f32_32x32x16_bf16 v[16:31], v[170:173], v[80:83], v[16:31]
	s_waitcnt lgkmcnt(3)
	v_mfma_f32_32x32x16_bf16 v[0:15], v[236:239], v[80:83], v[0:15]
	v_mfma_f32_32x32x16_bf16 v[48:63], v[100:103], v[88:91], v[48:63]
	v_mfma_f32_32x32x16_bf16 v[32:47], v[158:161], v[88:91], v[32:47]
	v_mfma_f32_32x32x16_bf16 v[16:31], v[174:177], v[88:91], v[16:31]
	s_waitcnt lgkmcnt(2)
	v_mfma_f32_32x32x16_bf16 v[0:15], v[240:243], v[88:91], v[0:15]
	v_mfma_f32_32x32x16_bf16 v[48:63], v[104:107], v[84:87], v[48:63]
	v_mfma_f32_32x32x16_bf16 v[32:47], v[162:165], v[84:87], v[32:47]
	v_mfma_f32_32x32x16_bf16 v[16:31], v[178:181], v[84:87], v[16:31]
	s_waitcnt lgkmcnt(1)
	v_mfma_f32_32x32x16_bf16 v[0:15], v[244:247], v[84:87], v[0:15]
	v_mfma_f32_32x32x16_bf16 v[48:63], v[108:111], v[92:95], v[48:63]
	v_mfma_f32_32x32x16_bf16 v[32:47], v[166:169], v[92:95], v[32:47]
	v_mfma_f32_32x32x16_bf16 v[16:31], v[232:235], v[92:95], v[16:31]
	s_waitcnt lgkmcnt(0)
	v_mfma_f32_32x32x16_bf16 v[0:15], v[248:251], v[92:95], v[0:15]
	s_mov_b32 s54, s52
	s_mov_b32 s55, s52
	s_mov_b32 s53, s52
	v_mov_b64_e32 v[186:187], s[54:55]
	v_mov_b64_e32 v[184:185], s[52:53]
	s_nop 1
	v_mfma_f32_32x32x16_bf16 v[64:79], v[184:187], v[80:83], v[64:79]
	v_mfma_f32_32x32x16_bf16 v[64:79], v[184:187], v[88:91], v[64:79]
	v_mfma_f32_32x32x16_bf16 v[64:79], v[184:187], v[84:87], v[64:79]
	v_mfma_f32_32x32x16_bf16 v[64:79], v[184:187], v[92:95], v[64:79]
	s_setprio 0

; #define LAS __attribute__((address_space(3)))
; #define MFMA32(a, b, c) __builtin_amdgcn_mfma_f32_32x32x16_bf16((a), (b), (c), 0, 0, 0)
; __device__ __forceinline__ void at_pv_half(const LAS unsigned char* vp, const bf16x8 (&pf)[4], f32x16 (&O)[4], f32x16& L) {
;     bf16x8 va[8], vb[8];
; #pragma unroll
;     for (int e = 0; e < 2; ++e)
; #pragma unroll
;         for (int ks = 0; ks < 4; ++ks) va[e * 4 + ks] = *(const LAS bf16x8*)(vp + e * 32 * AT_ROWB + 32 * ks);
; #pragma unroll
;     for (int e = 0; e < 2; ++e)
; #pragma unroll
;         for (int ks = 0; ks < 4; ++ks) vb[e * 4 + ks] = *(const LAS bf16x8*)(vp + (2 + e) * 32 * AT_ROWB + 32 * ks);
;     const short one = (short)0x3F80; const bf16x8 ones = {one, one, one, one, one, one, one, one};
;     __builtin_amdgcn_sched_barrier(0);
;     __builtin_amdgcn_s_setprio(1);
; #pragma unroll
;     for (int ks = 0; ks < 4; ++ks) L = MFMA32(ones, pf[ks], L);
;     __builtin_amdgcn_sched_barrier(0);
; #pragma unroll
;     for (int ks = 0; ks < 4; ++ks) { O[0] = MFMA32(va[ks], pf[ks], O[0]); O[1] = MFMA32(va[4 + ks], pf[ks], O[1]); }
; #pragma unroll
;     for (int ks = 0; ks < 4; ++ks) { O[2] = MFMA32(vb[ks], pf[ks], O[2]); O[3] = MFMA32(vb[4 + ks], pf[ks], O[3]); }
;     __builtin_amdgcn_s_setprio(0);
; }
.LBB0_307:
	s_lshl_b32 s0, s41, 6
	s_cmp_le_i32 s0, s40
	s_cbranch_scc0 .LBB0_309
	v_add_u32_e32 v166, 0, v228
	v_add_u32_e32 v184, 0xd800, v166
	ds_read_b128 v[96:99], v166 offset:55296
	ds_read_b128 v[100:103], v166 offset:55328
	ds_read_b128 v[104:107], v166 offset:55360
	ds_read_b128 v[108:111], v166 offset:55392
	s_waitcnt vmcnt(0)
	ds_read_b128 v[138:141], v166 offset:59904
	ds_read_b128 v[142:145], v166 offset:59936
	ds_read_b128 v[146:149], v166 offset:59968
	ds_read_b128 v[150:153], v166 offset:60000
	ds_read_b128 v[154:157], v166 offset:64512
	ds_read_b128 v[158:161], v166 offset:64544
	ds_read_b128 v[162:165], v166 offset:64576
	ds_read_b128 v[166:169], v166 offset:64608
	ds_read_b128 v[170:173], v184 offset:13824
	ds_read_b128 v[174:177], v184 offset:13856
	ds_read_b128 v[178:181], v184 offset:13888
	ds_read_b128 v[184:187], v184 offset:13920
	s_setprio 1
	s_waitcnt lgkmcnt(14)
	v_mfma_f32_32x32x16_bf16 v[48:63], v[96:99], v[80:83], v[48:63]
	s_waitcnt lgkmcnt(11)
	v_mfma_f32_32x32x16_bf16 v[32:47], v[138:141], v[80:83], v[32:47]
	s_waitcnt lgkmcnt(7)
	v_mfma_f32_32x32x16_bf16 v[16:31], v[154:157], v[80:83], v[16:31]
	s_waitcnt lgkmcnt(3)
	v_mfma_f32_32x32x16_bf16 v[0:15], v[170:173], v[80:83], v[0:15]
	v_mfma_f32_32x32x16_bf16 v[48:63], v[100:103], v[88:91], v[48:63]
	v_mfma_f32_32x32x16_bf16 v[32:47], v[142:145], v[88:91], v[32:47]
	v_mfma_f32_32x32x16_bf16 v[16:31], v[158:161], v[88:91], v[16:31]
	s_waitcnt lgkmcnt(2)
	v_mfma_f32_32x32x16_bf16 v[0:15], v[174:177], v[88:91], v[0:15]
	v_mfma_f32_32x32x16_bf16 v[48:63], v[104:107], v[84:87], v[48:63]
	v_mfma_f32_32x32x16_bf16 v[32:47], v[146:149], v[84:87], v[32:47]
	v_mfma_f32_32x32x16_bf16 v[16:31], v[162:165], v[84:87], v[16:31]
	s_waitcnt lgkmcnt(1)
	v_mfma_f32_32x32x16_bf16 v[0:15], v[178:181], v[84:87], v[0:15]
	v_mfma_f32_32x32x16_bf16 v[48:63], v[108:111], v[92:95], v[48:63]
	v_mfma_f32_32x32x16_bf16 v[32:47], v[150:153], v[92:95], v[32:47]
	v_mfma_f32_32x32x16_bf16 v[16:31], v[166:169], v[92:95], v[16:31]
	s_waitcnt lgkmcnt(0)
	v_mfma_f32_32x32x16_bf16 v[0:15], v[184:187], v[92:95], v[0:15]
	s_mov_b32 s54, s52
	s_mov_b32 s55, s52
	s_mov_b32 s53, s52
	v_mov_b64_e32 v[232:233], s[54:55]
	v_mov_b64_e32 v[230:231], s[52:53]
	s_nop 1
	v_mfma_f32_32x32x16_bf16 v[64:79], v[230:233], v[80:83], v[64:79]
	v_mfma_f32_32x32x16_bf16 v[64:79], v[230:233], v[88:91], v[64:79]
	v_mfma_f32_32x32x16_bf16 v[64:79], v[230:233], v[84:87], v[64:79]
	v_mfma_f32_32x32x16_bf16 v[64:79], v[230:233], v[92:95], v[64:79]
	s_setprio 0

; #define LAS __attribute__((address_space(3)))
; #define MFMA32(a, b, c) __builtin_amdgcn_mfma_f32_32x32x16_bf16((a), (b), (c), 0, 0, 0)
; #define AT_ISSUE_K(jn) do { const int jc_ = (jn) < ntm1 ? (jn) : ntm1; const size_t ko_ = (size_t)jc_ * 8192; ks0 = *(const u32x4*)(bK1 + ko_ + koff); ks1 = *(const u32x4*)(bK2 + ko_ + koff); } while (0)
; #define AT_WRITE_K(jn) do { LAS unsigned char* n_ = lds + ((jn) & 1) * AT_KST; *(LAS u32x4*)(n_ + dK1) = ks0; *(LAS u32x4*)(n_ + dK2) = ks1; } while (0)
; __device__ __forceinline__ void at_pv_half(const LAS unsigned char* vp, const bf16x8 (&pf)[4], f32x16 (&O)[4], f32x16& L) {
;     bf16x8 va[8], vb[8];
; #pragma unroll
;     for (int e = 0; e < 2; ++e)
; #pragma unroll
;         for (int ks = 0; ks < 4; ++ks) va[e * 4 + ks] = *(const LAS bf16x8*)(vp + e * 32 * AT_ROWB + 32 * ks);
; #pragma unroll
;     for (int e = 0; e < 2; ++e)
; #pragma unroll
;         for (int ks = 0; ks < 4; ++ks) vb[e * 4 + ks] = *(const LAS bf16x8*)(vp + (2 + e) * 32 * AT_ROWB + 32 * ks);
;     const short one = (short)0x3F80; const bf16x8 ones = {one, one, one, one, one, one, one, one};
;     __builtin_amdgcn_sched_barrier(0);
;     __builtin_amdgcn_s_setprio(1);
; #pragma unroll
;     for (int ks = 0; ks < 4; ++ks) L = MFMA32(ones, pf[ks], L);
;     __builtin_amdgcn_sched_barrier(0);
; #pragma unroll
;     for (int ks = 0; ks < 4; ++ks) { O[0] = MFMA32(va[ks], pf[ks], O[0]); O[1] = MFMA32(va[4 + ks], pf[ks], O[1]); }
; #pragma unroll
;     for (int ks = 0; ks < 4; ++ks) { O[2] = MFMA32(vb[ks], pf[ks], O[2]); O[3] = MFMA32(vb[4 + ks], pf[ks], O[3]); }
;     __builtin_amdgcn_s_setprio(0);
; }
; __device__ __forceinline__ void attn_item(LAS unsigned char* lds, const bf16_t* Q, const bf16_t* Kb, const bf16_t* VT, bf16_t* aout, const float* subg, float lam, float omli, float kbound, int head, int qb) {
;     ...
;             AT_WRITE_K(j + 1);
;             __syncthreads();
;             __builtin_amdgcn_s_setprio(0);
;             AT_ISSUE_K(j + 2);
.LBB0_320:
	s_setprio 0
	s_setprio 3
	s_bitcmp1_b32 s56, 0
	s_cselect_b32 s55, 0x4800, 0
	s_waitcnt lgkmcnt(7)
	v_add_u32_e32 v96, s55, v213
	s_waitcnt vmcnt(3)
	ds_write_b128 v96, v[130:133]
	s_waitcnt vmcnt(2)
	ds_write_b128 v96, v[134:137] offset:9216
	s_waitcnt lgkmcnt(0)
	s_barrier
	s_setprio 0
	s_add_i32 s53, s53, 2
	s_min_i32 s58, s53, s41
	s_lshl_b64 s[60:61], s[58:59], 13
	v_lshl_add_u64 v[98:99], v[204:205], 0, s[60:61]
	v_lshl_add_u64 v[100:101], v[206:207], 0, s[60:61]
	global_load_dwordx4 v[130:133], v[98:99], off
	global_load_dwordx4 v[134:137], v[100:101], off
	s_andn2_b64 vcc, exec, s[0:1]
	s_cbranch_vccnz .LBB0_322
	v_add_u32_e32 v97, s54, v228
	ds_read_b128 v[98:101], v97 offset:36864
	ds_read_b128 v[102:105], v97 offset:36896
	ds_read_b128 v[106:109], v97 offset:36928
	ds_read_b128 v[146:149], v97 offset:36960
	ds_read_b128 v[150:153], v97 offset:41472
	ds_read_b128 v[154:157], v97 offset:41504
	ds_read_b128 v[158:161], v97 offset:41536
	ds_read_b128 v[162:165], v97 offset:41568
	ds_read_b128 v[166:169], v97 offset:46080
	ds_read_b128 v[170:173], v97 offset:46112
	ds_read_b128 v[176:179], v97 offset:46144
	ds_read_b128 v[230:233], v97 offset:46176
	ds_read_b128 v[234:237], v97 offset:50688
	ds_read_b128 v[238:241], v97 offset:50720
	ds_read_b128 v[242:245], v97 offset:50752
	ds_read_b128 v[246:249], v97 offset:50784
	s_setprio 1
	s_waitcnt lgkmcnt(14)
	v_mfma_f32_32x32x16_bf16 v[48:63], v[98:101], v[80:83], v[48:63]
	s_waitcnt lgkmcnt(11)
	v_mfma_f32_32x32x16_bf16 v[32:47], v[150:153], v[80:83], v[32:47]
	s_waitcnt lgkmcnt(7)
	v_mfma_f32_32x32x16_bf16 v[16:31], v[166:169], v[80:83], v[16:31]
	s_waitcnt lgkmcnt(3)
	v_mfma_f32_32x32x16_bf16 v[0:15], v[234:237], v[80:83], v[0:15]
	v_mfma_f32_32x32x16_bf16 v[48:63], v[102:105], v[88:91], v[48:63]
	v_mfma_f32_32x32x16_bf16 v[32:47], v[154:157], v[88:91], v[32:47]
	v_mfma_f32_32x32x16_bf16 v[16:31], v[170:173], v[88:91], v[16:31]
	s_waitcnt lgkmcnt(2)
	v_mfma_f32_32x32x16_bf16 v[0:15], v[238:241], v[88:91], v[0:15]
	v_mfma_f32_32x32x16_bf16 v[48:63], v[106:109], v[84:87], v[48:63]
	v_mfma_f32_32x32x16_bf16 v[32:47], v[158:161], v[84:87], v[32:47]
	v_mfma_f32_32x32x16_bf16 v[16:31], v[176:179], v[84:87], v[16:31]
	s_waitcnt lgkmcnt(1)
	v_mfma_f32_32x32x16_bf16 v[0:15], v[242:245], v[84:87], v[0:15]
	v_mfma_f32_32x32x16_bf16 v[48:63], v[146:149], v[92:95], v[48:63]
	v_mfma_f32_32x32x16_bf16 v[32:47], v[162:165], v[92:95], v[32:47]
	v_mfma_f32_32x32x16_bf16 v[16:31], v[230:233], v[92:95], v[16:31]
	s_waitcnt lgkmcnt(0)
	v_mfma_f32_32x32x16_bf16 v[0:15], v[246:249], v[92:95], v[0:15]
	s_mov_b32 s54, s52
	s_mov_b32 s55, s52
	s_mov_b32 s53, s52
	v_mov_b64_e32 v[252:253], s[54:55]
	v_mov_b64_e32 v[250:251], s[52:53]
	s_nop 1
	v_mfma_f32_32x32x16_bf16 v[64:79], v[250:253], v[80:83], v[64:79]
	v_mfma_f32_32x32x16_bf16 v[64:79], v[250:253], v[88:91], v[64:79]
	v_mfma_f32_32x32x16_bf16 v[64:79], v[250:253], v[84:87], v[64:79]
	v_mfma_f32_32x32x16_bf16 v[64:79], v[250:253], v[92:95], v[64:79]
	s_setprio 0

; #define LAS __attribute__((address_space(3)))
; #define MFMA32(a, b, c) __builtin_amdgcn_mfma_f32_32x32x16_bf16((a), (b), (c), 0, 0, 0)
; __device__ __forceinline__ void at_pv_half(const LAS unsigned char* vp, const bf16x8 (&pf)[4], f32x16 (&O)[4], f32x16& L) {
;     bf16x8 va[8], vb[8];
; #pragma unroll
;     for (int e = 0; e < 2; ++e)
; #pragma unroll
;         for (int ks = 0; ks < 4; ++ks) va[e * 4 + ks] = *(const LAS bf16x8*)(vp + e * 32 * AT_ROWB + 32 * ks);
; #pragma unroll
;     for (int e = 0; e < 2; ++e)
; #pragma unroll
;         for (int ks = 0; ks < 4; ++ks) vb[e * 4 + ks] = *(const LAS bf16x8*)(vp + (2 + e) * 32 * AT_ROWB + 32 * ks);
;     const short one = (short)0x3F80; const bf16x8 ones = {one, one, one, one, one, one, one, one};
;     __builtin_amdgcn_sched_barrier(0);
;     __builtin_amdgcn_s_setprio(1);
; #pragma unroll
;     for (int ks = 0; ks < 4; ++ks) L = MFMA32(ones, pf[ks], L);
;     __builtin_amdgcn_sched_barrier(0);
; #pragma unroll
;     for (int ks = 0; ks < 4; ++ks) { O[0] = MFMA32(va[ks], pf[ks], O[0]); O[1] = MFMA32(va[4 + ks], pf[ks], O[1]); }
; #pragma unroll
;     for (int ks = 0; ks < 4; ++ks) { O[2] = MFMA32(vb[ks], pf[ks], O[2]); O[3] = MFMA32(vb[4 + ks], pf[ks], O[3]); }
;     __builtin_amdgcn_s_setprio(0);
; }
.LBB0_333:
	s_add_i32 s38, s39, 1
	s_bitcmp1_b32 s38, 0
	s_cselect_b32 s42, 0x4800, 0
	s_min_i32 s58, s38, s22
	s_lshl_b64 s[40:41], s[58:59], 14
	v_lshl_add_u64 v[96:97], v[208:209], 0, s[40:41]
	v_lshl_add_u64 v[98:99], v[210:211], 0, s[40:41]
	global_load_dwordx4 v[146:149], v[96:97], off
	global_load_dwordx4 v[150:153], v[98:99], off
	s_add_i32 s40, s42, 0
	s_cmp_eq_u32 s39, 0
	s_cselect_b64 s[42:43], -1, 0
	s_add_i32 s41, s1, 0xffffff81
	s_cmp_gt_i32 s41, s21
	s_cselect_b64 s[44:45], -1, 0
	s_or_b64 s[42:43], s[42:43], s[44:45]
	s_and_b64 vcc, exec, s[42:43]
	s_cbranch_vccnz .LBB0_335
	v_add_u32_e32 v244, s40, v228
	ds_read_b128 v[96:99], v244 offset:36864
	ds_read_b128 v[100:103], v244 offset:36896
	ds_read_b128 v[104:107], v244 offset:36928
	ds_read_b128 v[108:111], v244 offset:36960
	ds_read_b128 v[154:157], v244 offset:41472
	ds_read_b128 v[158:161], v244 offset:41504
	ds_read_b128 v[162:165], v244 offset:41536
	ds_read_b128 v[166:169], v244 offset:41568
	ds_read_b128 v[170:173], v244 offset:46080
	ds_read_b128 v[174:177], v244 offset:46112
	ds_read_b128 v[178:181], v244 offset:46144
	ds_read_b128 v[184:187], v244 offset:46176
	ds_read_b128 v[232:235], v244 offset:50688
	ds_read_b128 v[236:239], v244 offset:50720
	ds_read_b128 v[240:243], v244 offset:50752
	ds_read_b128 v[244:247], v244 offset:50784
	s_setprio 1
	s_waitcnt lgkmcnt(14)
	v_mfma_f32_32x32x16_bf16 v[48:63], v[96:99], v[80:83], v[48:63]
	s_waitcnt lgkmcnt(11)
	v_mfma_f32_32x32x16_bf16 v[32:47], v[154:157], v[80:83], v[32:47]
	s_waitcnt lgkmcnt(7)
	v_mfma_f32_32x32x16_bf16 v[16:31], v[170:173], v[80:83], v[16:31]
	s_waitcnt lgkmcnt(3)
	v_mfma_f32_32x32x16_bf16 v[0:15], v[232:235], v[80:83], v[0:15]
	v_mfma_f32_32x32x16_bf16 v[48:63], v[100:103], v[88:91], v[48:63]
	v_mfma_f32_32x32x16_bf16 v[32:47], v[158:161], v[88:91], v[32:47]
	v_mfma_f32_32x32x16_bf16 v[16:31], v[174:177], v[88:91], v[16:31]
	s_waitcnt lgkmcnt(2)
	v_mfma_f32_32x32x16_bf16 v[0:15], v[236:239], v[88:91], v[0:15]
	v_mfma_f32_32x32x16_bf16 v[48:63], v[104:107], v[84:87], v[48:63]
	v_mfma_f32_32x32x16_bf16 v[32:47], v[162:165], v[84:87], v[32:47]
	v_mfma_f32_32x32x16_bf16 v[16:31], v[178:181], v[84:87], v[16:31]
	s_waitcnt lgkmcnt(1)
	v_mfma_f32_32x32x16_bf16 v[0:15], v[240:243], v[84:87], v[0:15]
	v_mfma_f32_32x32x16_bf16 v[48:63], v[108:111], v[92:95], v[48:63]
	v_mfma_f32_32x32x16_bf16 v[32:47], v[166:169], v[92:95], v[32:47]
	v_mfma_f32_32x32x16_bf16 v[16:31], v[184:187], v[92:95], v[16:31]
	s_waitcnt lgkmcnt(0)
	v_mfma_f32_32x32x16_bf16 v[0:15], v[244:247], v[92:95], v[0:15]
	s_mov_b32 s54, s52
	s_mov_b32 s55, s52
	s_mov_b32 s53, s52
	v_mov_b64_e32 v[250:251], s[54:55]
	v_mov_b64_e32 v[248:249], s[52:53]
	s_nop 1
	v_mfma_f32_32x32x16_bf16 v[64:79], v[248:251], v[80:83], v[64:79]
	v_mfma_f32_32x32x16_bf16 v[64:79], v[248:251], v[88:91], v[64:79]
	v_mfma_f32_32x32x16_bf16 v[64:79], v[248:251], v[84:87], v[64:79]
	v_mfma_f32_32x32x16_bf16 v[64:79], v[248:251], v[92:95], v[64:79]
	s_setprio 0

; #define LAS __attribute__((address_space(3)))
; #define MFMA32(a, b, c) __builtin_amdgcn_mfma_f32_32x32x16_bf16((a), (b), (c), 0, 0, 0)
; __device__ __forceinline__ void at_pv_half(const LAS unsigned char* vp, const bf16x8 (&pf)[4], f32x16 (&O)[4], f32x16& L) {
;     bf16x8 va[8], vb[8];
; #pragma unroll
;     for (int e = 0; e < 2; ++e)
; #pragma unroll
;         for (int ks = 0; ks < 4; ++ks) va[e * 4 + ks] = *(const LAS bf16x8*)(vp + e * 32 * AT_ROWB + 32 * ks);
; #pragma unroll
;     for (int e = 0; e < 2; ++e)
; #pragma unroll
;         for (int ks = 0; ks < 4; ++ks) vb[e * 4 + ks] = *(const LAS bf16x8*)(vp + (2 + e) * 32 * AT_ROWB + 32 * ks);
;     const short one = (short)0x3F80; const bf16x8 ones = {one, one, one, one, one, one, one, one};
;     __builtin_amdgcn_sched_barrier(0);
;     __builtin_amdgcn_s_setprio(1);
; #pragma unroll
;     for (int ks = 0; ks < 4; ++ks) L = MFMA32(ones, pf[ks], L);
;     __builtin_amdgcn_sched_barrier(0);
; #pragma unroll
;     for (int ks = 0; ks < 4; ++ks) { O[0] = MFMA32(va[ks], pf[ks], O[0]); O[1] = MFMA32(va[4 + ks], pf[ks], O[1]); }
; #pragma unroll
;     for (int ks = 0; ks < 4; ++ks) { O[2] = MFMA32(vb[ks], pf[ks], O[2]); O[3] = MFMA32(vb[4 + ks], pf[ks], O[3]); }
;     __builtin_amdgcn_s_setprio(0);
; }
.LBB0_345:
	s_lshl_b32 s0, s22, 6
	s_cmp_le_i32 s0, s21
	s_cbranch_scc0 .LBB0_347
	v_add_u32_e32 v166, 0, v228
	v_add_u32_e32 v184, 0xd800, v166
	ds_read_b128 v[96:99], v166 offset:55296
	ds_read_b128 v[100:103], v166 offset:55328
	ds_read_b128 v[104:107], v166 offset:55360
	ds_read_b128 v[108:111], v166 offset:55392
	s_waitcnt vmcnt(0)
	ds_read_b128 v[138:141], v166 offset:59904
	ds_read_b128 v[142:145], v166 offset:59936
	ds_read_b128 v[146:149], v166 offset:59968
	ds_read_b128 v[150:153], v166 offset:60000
	ds_read_b128 v[154:157], v166 offset:64512
	ds_read_b128 v[158:161], v166 offset:64544
	ds_read_b128 v[162:165], v166 offset:64576
	ds_read_b128 v[166:169], v166 offset:64608
	ds_read_b128 v[170:173], v184 offset:13824
	ds_read_b128 v[174:177], v184 offset:13856
	ds_read_b128 v[178:181], v184 offset:13888
	ds_read_b128 v[184:187], v184 offset:13920
	s_setprio 1
	s_waitcnt lgkmcnt(14)
	v_mfma_f32_32x32x16_bf16 v[48:63], v[96:99], v[80:83], v[48:63]
	s_waitcnt lgkmcnt(11)
	v_mfma_f32_32x32x16_bf16 v[32:47], v[138:141], v[80:83], v[32:47]
	s_waitcnt lgkmcnt(7)
	v_mfma_f32_32x32x16_bf16 v[16:31], v[154:157], v[80:83], v[16:31]
	s_waitcnt lgkmcnt(3)
	v_mfma_f32_32x32x16_bf16 v[0:15], v[170:173], v[80:83], v[0:15]
	v_mfma_f32_32x32x16_bf16 v[48:63], v[100:103], v[88:91], v[48:63]
	v_mfma_f32_32x32x16_bf16 v[32:47], v[142:145], v[88:91], v[32:47]
	v_mfma_f32_32x32x16_bf16 v[16:31], v[158:161], v[88:91], v[16:31]
	s_waitcnt lgkmcnt(2)
	v_mfma_f32_32x32x16_bf16 v[0:15], v[174:177], v[88:91], v[0:15]
	v_mfma_f32_32x32x16_bf16 v[48:63], v[104:107], v[84:87], v[48:63]
	v_mfma_f32_32x32x16_bf16 v[32:47], v[146:149], v[84:87], v[32:47]
	v_mfma_f32_32x32x16_bf16 v[16:31], v[162:165], v[84:87], v[16:31]
	s_waitcnt lgkmcnt(1)
	v_mfma_f32_32x32x16_bf16 v[0:15], v[178:181], v[84:87], v[0:15]
	v_mfma_f32_32x32x16_bf16 v[48:63], v[108:111], v[92:95], v[48:63]
	v_mfma_f32_32x32x16_bf16 v[32:47], v[150:153], v[92:95], v[32:47]
	v_mfma_f32_32x32x16_bf16 v[16:31], v[166:169], v[92:95], v[16:31]
	s_waitcnt lgkmcnt(0)
	v_mfma_f32_32x32x16_bf16 v[0:15], v[184:187], v[92:95], v[0:15]
	s_mov_b32 s54, s52
	s_mov_b32 s55, s52
	s_mov_b32 s53, s52
	v_mov_b64_e32 v[232:233], s[54:55]
	v_mov_b64_e32 v[230:231], s[52:53]
	s_nop 1
	v_mfma_f32_32x32x16_bf16 v[64:79], v[230:233], v[80:83], v[64:79]
	v_mfma_f32_32x32x16_bf16 v[64:79], v[230:233], v[88:91], v[64:79]
	v_mfma_f32_32x32x16_bf16 v[64:79], v[230:233], v[84:87], v[64:79]
	v_mfma_f32_32x32x16_bf16 v[64:79], v[230:233], v[92:95], v[64:79]
	s_setprio 0

; #define LAS __attribute__((address_space(3)))
; #define MFMA32(a, b, c) __builtin_amdgcn_mfma_f32_32x32x16_bf16((a), (b), (c), 0, 0, 0)
; #define AT_ISSUE_K(jn) do { const int jc_ = (jn) < ntm1 ? (jn) : ntm1; const size_t ko_ = (size_t)jc_ * 8192; ks0 = *(const u32x4*)(bK1 + ko_ + koff); ks1 = *(const u32x4*)(bK2 + ko_ + koff); } while (0)
; #define AT_WRITE_K(jn) do { LAS unsigned char* n_ = lds + ((jn) & 1) * AT_KST; *(LAS u32x4*)(n_ + dK1) = ks0; *(LAS u32x4*)(n_ + dK2) = ks1; } while (0)
; __device__ __forceinline__ void at_pv_half(const LAS unsigned char* vp, const bf16x8 (&pf)[4], f32x16 (&O)[4], f32x16& L) {
;     bf16x8 va[8], vb[8];
; #pragma unroll
;     for (int e = 0; e < 2; ++e)
; #pragma unroll
;         for (int ks = 0; ks < 4; ++ks) va[e * 4 + ks] = *(const LAS bf16x8*)(vp + e * 32 * AT_ROWB + 32 * ks);
; #pragma unroll
;     for (int e = 0; e < 2; ++e)
; #pragma unroll
;         for (int ks = 0; ks < 4; ++ks) vb[e * 4 + ks] = *(const LAS bf16x8*)(vp + (2 + e) * 32 * AT_ROWB + 32 * ks);
;     const short one = (short)0x3F80; const bf16x8 ones = {one, one, one, one, one, one, one, one};
;     __builtin_amdgcn_sched_barrier(0);
;     __builtin_amdgcn_s_setprio(1);
; #pragma unroll
;     for (int ks = 0; ks < 4; ++ks) L = MFMA32(ones, pf[ks], L);
;     __builtin_amdgcn_sched_barrier(0);
; #pragma unroll
;     for (int ks = 0; ks < 4; ++ks) { O[0] = MFMA32(va[ks], pf[ks], O[0]); O[1] = MFMA32(va[4 + ks], pf[ks], O[1]); }
; #pragma unroll
;     for (int ks = 0; ks < 4; ++ks) { O[2] = MFMA32(vb[ks], pf[ks], O[2]); O[3] = MFMA32(vb[4 + ks], pf[ks], O[3]); }
;     __builtin_amdgcn_s_setprio(0);
; }
; __device__ __forceinline__ void attn_item(LAS unsigned char* lds, const bf16_t* Q, const bf16_t* Kb, const bf16_t* VT, bf16_t* aout, const float* subg, float lam, float omli, float kbound, int head, int qb) {
;     ...
;             AT_WRITE_K(j + 1);
;             __syncthreads();
;             __builtin_amdgcn_s_setprio(0);
;             AT_ISSUE_K(j + 2);
.LBB0_358:
	s_setprio 0
	s_setprio 3
	s_bitcmp1_b32 s39, 0
	s_cselect_b32 s41, 0x4800, 0
	s_waitcnt lgkmcnt(7)
	v_add_u32_e32 v96, s41, v213
	s_waitcnt vmcnt(3)
	ds_write_b128 v96, v[130:133]
	s_waitcnt vmcnt(2)
	ds_write_b128 v96, v[134:137] offset:9216
	s_waitcnt lgkmcnt(0)
	s_barrier
	s_setprio 0
	s_add_i32 s38, s38, 2
	s_min_i32 s58, s38, s22
	s_lshl_b64 s[42:43], s[58:59], 13
	v_lshl_add_u64 v[98:99], v[204:205], 0, s[42:43]
	v_lshl_add_u64 v[100:101], v[206:207], 0, s[42:43]
	global_load_dwordx4 v[130:133], v[98:99], off
	global_load_dwordx4 v[134:137], v[100:101], off
	s_andn2_b64 vcc, exec, s[0:1]
	s_cbranch_vccnz .LBB0_360
	v_add_u32_e32 v97, s40, v228
	ds_read_b128 v[98:101], v97 offset:36864
	ds_read_b128 v[102:105], v97 offset:36896
	ds_read_b128 v[106:109], v97 offset:36928
	ds_read_b128 v[146:149], v97 offset:36960
	ds_read_b128 v[150:153], v97 offset:41472
	ds_read_b128 v[154:157], v97 offset:41504
	ds_read_b128 v[158:161], v97 offset:41536
	ds_read_b128 v[162:165], v97 offset:41568
	ds_read_b128 v[166:169], v97 offset:46080
	ds_read_b128 v[170:173], v97 offset:46112
	ds_read_b128 v[176:179], v97 offset:46144
	ds_read_b128 v[184:187], v97 offset:46176
	ds_read_b128 v[230:233], v97 offset:50688
	ds_read_b128 v[234:237], v97 offset:50720
	ds_read_b128 v[238:241], v97 offset:50752
	ds_read_b128 v[242:245], v97 offset:50784
	s_setprio 1
	s_waitcnt lgkmcnt(14)
	v_mfma_f32_32x32x16_bf16 v[48:63], v[98:101], v[80:83], v[48:63]
	s_waitcnt lgkmcnt(11)
	v_mfma_f32_32x32x16_bf16 v[32:47], v[150:153], v[80:83], v[32:47]
	s_waitcnt lgkmcnt(7)
	v_mfma_f32_32x32x16_bf16 v[16:31], v[166:169], v[80:83], v[16:31]
	s_waitcnt lgkmcnt(3)
	v_mfma_f32_32x32x16_bf16 v[0:15], v[230:233], v[80:83], v[0:15]
	v_mfma_f32_32x32x16_bf16 v[48:63], v[102:105], v[88:91], v[48:63]
	v_mfma_f32_32x32x16_bf16 v[32:47], v[154:157], v[88:91], v[32:47]
	v_mfma_f32_32x32x16_bf16 v[16:31], v[170:173], v[88:91], v[16:31]
	s_waitcnt lgkmcnt(2)
	v_mfma_f32_32x32x16_bf16 v[0:15], v[234:237], v[88:91], v[0:15]
	v_mfma_f32_32x32x16_bf16 v[48:63], v[106:109], v[84:87], v[48:63]
	v_mfma_f32_32x32x16_bf16 v[32:47], v[158:161], v[84:87], v[32:47]
	v_mfma_f32_32x32x16_bf16 v[16:31], v[176:179], v[84:87], v[16:31]
	s_waitcnt lgkmcnt(1)
	v_mfma_f32_32x32x16_bf16 v[0:15], v[238:241], v[84:87], v[0:15]
	v_mfma_f32_32x32x16_bf16 v[48:63], v[146:149], v[92:95], v[48:63]
	v_mfma_f32_32x32x16_bf16 v[32:47], v[162:165], v[92:95], v[32:47]
	v_mfma_f32_32x32x16_bf16 v[16:31], v[184:187], v[92:95], v[16:31]
	s_waitcnt lgkmcnt(0)
	v_mfma_f32_32x32x16_bf16 v[0:15], v[242:245], v[92:95], v[0:15]
	s_mov_b32 s54, s52
	s_mov_b32 s55, s52
	s_mov_b32 s53, s52
	v_mov_b64_e32 v[248:249], s[54:55]
	v_mov_b64_e32 v[246:247], s[52:53]
	s_nop 1
	v_mfma_f32_32x32x16_bf16 v[64:79], v[246:249], v[80:83], v[64:79]
	v_mfma_f32_32x32x16_bf16 v[64:79], v[246:249], v[88:91], v[64:79]
	v_mfma_f32_32x32x16_bf16 v[64:79], v[246:249], v[84:87], v[64:79]
	v_mfma_f32_32x32x16_bf16 v[64:79], v[246:249], v[92:95], v[64:79]
	s_setprio 0
